# MLA fast loop: the MFMA segment's store addresses and K base are computed at the end of the same wave's preceding softmax segment (4 VALU) instead of in the previous K.Q^T shadows
# speedup vs baseline: 1.0005x; 1.0005x over previous
.Lfm_a_exp:
	v_exp_f32_e32 v34, v34
	v_exp_f32_e32 v50, v50
	v_exp_f32_e32 v35, v35
	v_exp_f32_e32 v51, v51
	v_exp_f32_e32 v42, v42
	v_exp_f32_e32 v58, v58
	v_exp_f32_e32 v43, v43
	v_exp_f32_e32 v59, v59
	v_exp_f32_e32 v36, v36
	v_exp_f32_e32 v52, v52
	v_exp_f32_e32 v37, v37
	v_exp_f32_e32 v53, v53
	v_exp_f32_e32 v44, v44
	v_exp_f32_e32 v60, v60
	v_exp_f32_e32 v45, v45
	v_exp_f32_e32 v61, v61
	v_exp_f32_e32 v38, v38
	v_exp_f32_e32 v54, v54
	v_exp_f32_e32 v39, v39
	v_exp_f32_e32 v55, v55
	v_exp_f32_e32 v46, v46
	v_exp_f32_e32 v62, v62
	v_exp_f32_e32 v47, v47
	v_exp_f32_e32 v63, v63
	v_exp_f32_e32 v40, v40
	v_exp_f32_e32 v56, v56
	v_exp_f32_e32 v41, v41
	v_exp_f32_e32 v57, v57
	v_exp_f32_e32 v48, v48
	v_exp_f32_e32 v64, v64
	v_exp_f32_e32 v49, v49
	v_exp_f32_e32 v65, v65
	v_pk_add_f32 v[122:123], v[34:35], v[50:51]
	v_pk_add_f32 v[124:125], v[36:37], v[52:53]
	v_pk_add_f32 v[126:127], v[38:39], v[54:55]
	v_pk_add_f32 v[128:129], v[40:41], v[56:57]
	v_pk_add_f32 v[130:131], v[42:43], v[58:59]
	v_pk_add_f32 v[132:133], v[44:45], v[60:61]
	v_pk_add_f32 v[134:135], v[46:47], v[62:63]
	v_pk_add_f32 v[136:137], v[48:49], v[64:65]
	v_pk_add_f32 v[122:123], v[122:123], v[124:125]
	v_pk_add_f32 v[126:127], v[126:127], v[128:129]
	v_pk_add_f32 v[130:131], v[130:131], v[132:133]
	v_pk_add_f32 v[134:135], v[134:135], v[136:137]
	v_pk_add_f32 v[122:123], v[122:123], v[126:127]
	v_pk_add_f32 v[130:131], v[130:131], v[134:135]
	v_pk_add_f32 v[122:123], v[122:123], v[130:131]
	v_add_f32_e32 v0, v122, v123
	v_cvt_pk_bf16_f32 v122, v34, v35
	v_cvt_pk_bf16_f32 v123, v36, v37
	v_cvt_pk_bf16_f32 v124, v38, v39
	v_cvt_pk_bf16_f32 v125, v40, v41
	v_cvt_pk_bf16_f32 v126, v42, v43
	v_cvt_pk_bf16_f32 v127, v44, v45
	v_cvt_pk_bf16_f32 v128, v46, v47
	v_cvt_pk_bf16_f32 v129, v48, v49
	v_cvt_pk_bf16_f32 v130, v50, v51
	v_cvt_pk_bf16_f32 v131, v52, v53
	v_cvt_pk_bf16_f32 v132, v54, v55
	v_cvt_pk_bf16_f32 v133, v56, v57
	v_cvt_pk_bf16_f32 v134, v58, v59
	v_cvt_pk_bf16_f32 v135, v60, v61
	v_cvt_pk_bf16_f32 v136, v62, v63
	v_cvt_pk_bf16_f32 v137, v64, v65
	v_add_f32_e32 v162, v162, v0
	v_add3_u32 v190, s57, v152, v153
	v_add3_u32 v192, s57, v154, v155
	v_add3_u32 v194, s57, v156, v140
	v_add_u32_e32 v195, s60, v157
	s_waitcnt lgkmcnt(0)
	s_barrier
	v_mfma_f32_32x32x16_bf16 v[2:17], v[164:167], v[122:125], v[2:17]
	s_setprio 1
	s_waitcnt vmcnt(3)
	ds_write_b128 v190, v[86:89]
	v_mfma_f32_32x32x16_bf16 v[18:33], v[168:171], v[122:125], v[18:33]
	ds_write_b128 v192, v[90:93]
	v_mfma_f32_32x32x16_bf16 v[2:17], v[172:175], v[126:129], v[2:17]
	ds_write_b128 v194, v[82:85] offset:13312
	v_mfma_f32_32x32x16_bf16 v[18:33], v[176:179], v[126:129], v[18:33]
	ds_read_b128 v[236:239], v195
	ds_read_b128 v[240:243], v195 offset:6656
	ds_read_b128 v[244:247], v195 offset:32
	v_mfma_f32_32x32x16_bf16 v[2:17], v[180:183], v[130:133], v[2:17]
	ds_read_b128 v[164:167], v195 offset:6688
	ds_read_b128 v[168:171], v195 offset:64
	ds_read_b128 v[172:175], v195 offset:6720
	v_mfma_f32_32x32x16_bf16 v[18:33], v[220:223], v[130:133], v[18:33]
	ds_read_b128 v[176:179], v195 offset:96
	ds_read_b128 v[180:183], v195 offset:6752
	ds_read_b128 v[220:223], v195 offset:128
	v_mfma_f32_32x32x16_bf16 v[2:17], v[224:227], v[134:137], v[2:17]
	ds_read_b128 v[224:227], v195 offset:6784
	v_mfma_f32_32x32x16_bf16 v[18:33], v[232:235], v[134:137], v[18:33]
	ds_read_b128 v[232:235], v195 offset:160
	s_waitcnt lgkmcnt(9)
	v_mfma_f32_32x32x16_bf16 v[34:49], v[236:239], v[196:199], v[66:81]
	ds_read_b128 v[236:239], v195 offset:6816
	v_mfma_f32_32x32x16_bf16 v[50:65], v[240:243], v[196:199], v[66:81]
	s_waitcnt lgkmcnt(7)
	v_mfma_f32_32x32x16_bf16 v[34:49], v[244:247], v[200:203], v[34:49]
	v_add_u32_e32 v248, s60, v160
	s_add_i32 s0, s59, 4
	s_lshl_b32 s8, s0, 6
	v_mfma_f32_32x32x16_bf16 v[50:65], v[164:167], v[200:203], v[50:65]
	ds_read_b128 v[164:167], v248 offset:13312
	s_mul_i32 s0, s8, 0x600
	s_mov_b32 s1, 0
	v_mfma_f32_32x32x16_bf16 v[34:49], v[168:171], v[204:207], v[34:49]
	ds_read_b128 v[168:171], v248 offset:17920
	v_lshl_add_u64 v[82:83], s[0:1], 0, v[186:187]
	v_lshl_add_u64 v[84:85], s[0:1], 0, v[188:189]
	s_waitcnt lgkmcnt(6)
	v_mfma_f32_32x32x16_bf16 v[50:65], v[172:175], v[204:207], v[50:65]
	ds_read_b128 v[172:175], v248 offset:13344
	global_load_dwordx4 v[86:89], v[82:83], off
	global_load_dwordx4 v[90:93], v[84:85], off
	v_mfma_f32_32x32x16_bf16 v[34:49], v[176:179], v[208:211], v[34:49]
	ds_read_b128 v[176:179], v248 offset:17952
	v_lshl_add_u64 v[82:83], s[8:9], 1, v[142:143]
	global_load_dwordx4 v[82:85], v[82:83], off
	v_mfma_f32_32x32x16_bf16 v[50:65], v[180:183], v[208:211], v[50:65]
	ds_read_b128 v[180:183], v248 offset:13376
	s_waitcnt lgkmcnt(6)
	v_mfma_f32_32x32x16_bf16 v[34:49], v[220:223], v[212:215], v[34:49]
	ds_read_b128 v[220:223], v248 offset:17984
	v_mfma_f32_32x32x16_bf16 v[50:65], v[224:227], v[212:215], v[50:65]
	ds_read_b128 v[224:227], v248 offset:13408
	v_mfma_f32_32x32x16_bf16 v[34:49], v[232:235], v[216:219], v[34:49]
	ds_read_b128 v[232:235], v248 offset:18016
	s_waitcnt lgkmcnt(8)
	v_mfma_f32_32x32x16_bf16 v[50:65], v[236:239], v[216:219], v[50:65]
	s_setprio 0
	s_waitcnt lgkmcnt(8)
	s_barrier
	v_max3_f32 v0, v34, v35, v36
	v_max3_f32 v106, v50, v51, v52
	v_max3_f32 v0, v0, v37, v38
	v_max3_f32 v106, v106, v53, v54
	v_max3_f32 v0, v0, v39, v40
	v_max3_f32 v106, v106, v55, v56
	v_max3_f32 v0, v0, v41, v42
	v_max3_f32 v106, v106, v57, v58
	v_max3_f32 v0, v0, v43, v44
	v_max3_f32 v106, v106, v59, v60
	v_max3_f32 v0, v0, v45, v46
	v_max3_f32 v106, v106, v61, v62
	v_max3_f32 v0, v0, v47, v48
	v_max3_f32 v106, v106, v63, v64
	v_max3_f32 v0, v0, v106, v49
	v_max_f32_e32 v0, v0, v65
	v_cmp_lt_f32_e32 vcc, s35, v0
	s_cbranch_vccnz .Lfm_b_resc
.Lfm_b_exp:
	v_exp_f32_e32 v34, v34
	v_exp_f32_e32 v50, v50
	v_exp_f32_e32 v35, v35
	v_exp_f32_e32 v51, v51
	v_exp_f32_e32 v42, v42
	v_exp_f32_e32 v58, v58
	v_exp_f32_e32 v43, v43
	v_exp_f32_e32 v59, v59
	v_exp_f32_e32 v36, v36
	v_exp_f32_e32 v52, v52
	v_exp_f32_e32 v37, v37
	v_exp_f32_e32 v53, v53
	v_exp_f32_e32 v44, v44
	v_exp_f32_e32 v60, v60
	v_exp_f32_e32 v45, v45
	v_exp_f32_e32 v61, v61
	v_exp_f32_e32 v38, v38
	v_exp_f32_e32 v54, v54
	v_exp_f32_e32 v39, v39
	v_exp_f32_e32 v55, v55
	v_exp_f32_e32 v46, v46
	v_exp_f32_e32 v62, v62
	v_exp_f32_e32 v47, v47
	v_exp_f32_e32 v63, v63
	v_exp_f32_e32 v40, v40
	v_exp_f32_e32 v56, v56
	v_exp_f32_e32 v41, v41
	v_exp_f32_e32 v57, v57
	v_exp_f32_e32 v48, v48
	v_exp_f32_e32 v64, v64
	v_exp_f32_e32 v49, v49
	v_exp_f32_e32 v65, v65
	v_pk_add_f32 v[106:107], v[34:35], v[50:51]
	v_pk_add_f32 v[108:109], v[36:37], v[52:53]
	v_pk_add_f32 v[110:111], v[38:39], v[54:55]
	v_pk_add_f32 v[112:113], v[40:41], v[56:57]
	v_pk_add_f32 v[114:115], v[42:43], v[58:59]
	v_pk_add_f32 v[116:117], v[44:45], v[60:61]
	v_pk_add_f32 v[118:119], v[46:47], v[62:63]
	v_pk_add_f32 v[120:121], v[48:49], v[64:65]
	v_pk_add_f32 v[106:107], v[106:107], v[108:109]
	v_pk_add_f32 v[110:111], v[110:111], v[112:113]
	v_pk_add_f32 v[114:115], v[114:115], v[116:117]
	v_pk_add_f32 v[118:119], v[118:119], v[120:121]
	v_pk_add_f32 v[106:107], v[106:107], v[110:111]
	v_pk_add_f32 v[114:115], v[114:115], v[118:119]
	v_pk_add_f32 v[106:107], v[106:107], v[114:115]
	v_add_f32_e32 v0, v106, v107
	v_cvt_pk_bf16_f32 v106, v34, v35
	v_cvt_pk_bf16_f32 v107, v36, v37
	v_cvt_pk_bf16_f32 v108, v38, v39
	v_cvt_pk_bf16_f32 v109, v40, v41
	v_cvt_pk_bf16_f32 v110, v42, v43
	v_cvt_pk_bf16_f32 v111, v44, v45
	v_cvt_pk_bf16_f32 v112, v46, v47
	v_cvt_pk_bf16_f32 v113, v48, v49
	v_cvt_pk_bf16_f32 v114, v50, v51
	v_cvt_pk_bf16_f32 v115, v52, v53
	v_cvt_pk_bf16_f32 v116, v54, v55
	v_cvt_pk_bf16_f32 v117, v56, v57
	v_cvt_pk_bf16_f32 v118, v58, v59
	v_cvt_pk_bf16_f32 v119, v60, v61
	v_cvt_pk_bf16_f32 v120, v62, v63
	v_cvt_pk_bf16_f32 v121, v64, v65
	v_add_f32_e32 v162, v162, v0
	v_add3_u32 v190, s58, v152, v153
	v_add3_u32 v192, s58, v154, v155
	v_add3_u32 v194, s58, v156, v140
	v_add_u32_e32 v195, s57, v157
	s_waitcnt lgkmcnt(0)
	s_barrier
	v_mfma_f32_32x32x16_bf16 v[2:17], v[164:167], v[106:109], v[2:17]
	s_setprio 1
	s_waitcnt vmcnt(3)
	ds_write_b128 v190, v[98:101]
	v_mfma_f32_32x32x16_bf16 v[18:33], v[168:171], v[106:109], v[18:33]
	ds_write_b128 v192, v[94:97]
	v_mfma_f32_32x32x16_bf16 v[2:17], v[172:175], v[110:113], v[2:17]
	ds_write_b128 v194, v[102:105] offset:13312
	v_mfma_f32_32x32x16_bf16 v[18:33], v[176:179], v[110:113], v[18:33]
	ds_read_b128 v[236:239], v195
	ds_read_b128 v[240:243], v195 offset:6656
	ds_read_b128 v[244:247], v195 offset:32
	v_mfma_f32_32x32x16_bf16 v[2:17], v[180:183], v[114:117], v[2:17]
	ds_read_b128 v[164:167], v195 offset:6688
	ds_read_b128 v[168:171], v195 offset:64
	ds_read_b128 v[172:175], v195 offset:6720
	v_mfma_f32_32x32x16_bf16 v[18:33], v[220:223], v[114:117], v[18:33]
	ds_read_b128 v[176:179], v195 offset:96
	ds_read_b128 v[180:183], v195 offset:6752
	ds_read_b128 v[220:223], v195 offset:128
	v_mfma_f32_32x32x16_bf16 v[2:17], v[224:227], v[118:121], v[2:17]
	ds_read_b128 v[224:227], v195 offset:6784
	v_mfma_f32_32x32x16_bf16 v[18:33], v[232:235], v[118:121], v[18:33]
	ds_read_b128 v[232:235], v195 offset:160
	s_waitcnt lgkmcnt(9)
	v_mfma_f32_32x32x16_bf16 v[34:49], v[236:239], v[196:199], v[66:81]
	ds_read_b128 v[236:239], v195 offset:6816
	s_add_i32 s59, s59, 2
	s_mov_b32 s0, s58
	v_mfma_f32_32x32x16_bf16 v[50:65], v[240:243], v[196:199], v[66:81]
	s_mov_b32 s58, s57
	s_mov_b32 s57, s60
	s_mov_b32 s60, s0
	s_waitcnt lgkmcnt(7)
	v_mfma_f32_32x32x16_bf16 v[34:49], v[244:247], v[200:203], v[34:49]
	s_addk_i32 s54, 0x80
	v_add_u32_e32 v248, s58, v160
	s_add_i32 s1, s59, 3
	s_lshl_b32 s8, s1, 6
	v_mfma_f32_32x32x16_bf16 v[50:65], v[164:167], v[200:203], v[50:65]
	ds_read_b128 v[164:167], v248 offset:13312
	s_mul_i32 s20, s8, 0x600
	s_mov_b32 s21, 0
	v_mfma_f32_32x32x16_bf16 v[34:49], v[168:171], v[204:207], v[34:49]
	ds_read_b128 v[168:171], v248 offset:17920
	v_lshl_add_u64 v[94:95], s[20:21], 0, v[186:187]
	v_lshl_add_u64 v[96:97], s[20:21], 0, v[188:189]
	s_waitcnt lgkmcnt(6)
	v_mfma_f32_32x32x16_bf16 v[50:65], v[172:175], v[204:207], v[50:65]
	ds_read_b128 v[172:175], v248 offset:13344
	v_lshl_add_u64 v[102:103], s[8:9], 1, v[142:143]
	global_load_dwordx4 v[98:101], v[94:95], off
	v_mfma_f32_32x32x16_bf16 v[34:49], v[176:179], v[208:211], v[34:49]
	ds_read_b128 v[176:179], v248 offset:17952
	s_nop 0
	global_load_dwordx4 v[94:97], v[96:97], off
	global_load_dwordx4 v[102:105], v[102:103], off
	v_mfma_f32_32x32x16_bf16 v[50:65], v[180:183], v[208:211], v[50:65]
	ds_read_b128 v[180:183], v248 offset:13376
	s_waitcnt lgkmcnt(6)
	v_mfma_f32_32x32x16_bf16 v[34:49], v[220:223], v[212:215], v[34:49]
	ds_read_b128 v[220:223], v248 offset:17984
	v_mfma_f32_32x32x16_bf16 v[50:65], v[224:227], v[212:215], v[50:65]
	ds_read_b128 v[224:227], v248 offset:13408
	v_mfma_f32_32x32x16_bf16 v[34:49], v[232:235], v[216:219], v[34:49]
	ds_read_b128 v[232:235], v248 offset:18016
	s_waitcnt lgkmcnt(8)
	v_mfma_f32_32x32x16_bf16 v[50:65], v[236:239], v[216:219], v[50:65]
	s_setprio 0
	s_add_i32 s4, s55, s59
	s_cmp_lt_i32 s4, -1
	s_waitcnt lgkmcnt(8)
	s_barrier
	s_cbranch_scc1 .Lfm_head
	s_mov_b32 s0, s58
	s_mov_b32 s58, s60
	s_branch .LBB0_1037
